# P1 K-loop back-edge rotation: counter update and next-iteration pointer selects moved from the loop head into the light fourth load segment
# baseline (speedup 1.0000x reference)
.LBB0_170:
	s_add_u32 s10, s8, 0xfffc0080
	s_addc_u32 s11, s9, -1
	s_add_i32 s30, 0, 0x10000
	s_cmp_eq_u32 s29, 12
	s_cselect_b32 s13, s3, s11
	s_cselect_b32 s12, s24, s10
	s_cselect_b32 s11, s25, s28
	s_cselect_b32 s10, s26, s27
	s_add_i32 s31, 0, 0x14000
.Lk1_body:
	v_add_u32_e32 v0, s30, v197
	ds_read_b128 v[130:133], v0
	ds_read_b128 v[134:137], v0 offset:1024
	ds_read_b128 v[138:141], v0 offset:2048
	ds_read_b128 v[142:145], v0 offset:3072
	v_add_u32_e32 v0, s31, v197
	ds_read_b128 v[170:173], v0
	ds_read_b128 v[174:177], v0 offset:1024
	ds_read_b128 v[202:205], v0 offset:2048
	ds_read_b128 v[206:209], v0 offset:3072
	s_add_i32 m0, s59, 0xc000
	ds_read_b128 v[210:213], v200
	ds_read_b128 v[216:219], v200 offset:1024
	ds_read_b128 v[220:223], v200 offset:2048
	ds_read_b128 v[224:227], v200 offset:3072
	ds_read_b128 v[228:231], v200 offset:4096
	ds_read_b128 v[232:235], v200 offset:5120
	ds_read_b128 v[236:239], v200 offset:6144
	ds_read_b128 v[240:243], v200 offset:7168
	global_load_lds_dwordx4 v166, s[8:9]
	s_add_i32 m0, s59, 0xe000
	s_nop 0
	global_load_lds_dwordx4 v168, s[8:9]
	s_waitcnt vmcnt(8)
	s_waitcnt lgkmcnt(0)
	s_barrier
	s_setprio 1
	s_waitcnt lgkmcnt(0)
	v_mfma_f32_16x16x32_bf16 v[126:129], v[130:133], v[210:213], v[126:129]
	v_mfma_f32_16x16x32_bf16 v[122:125], v[138:141], v[210:213], v[122:125]
	v_mfma_f32_16x16x32_bf16 v[110:113], v[130:133], v[220:223], v[110:113]
	v_mfma_f32_16x16x32_bf16 v[106:109], v[138:141], v[220:223], v[106:109]
	v_mfma_f32_16x16x32_bf16 v[94:97], v[130:133], v[228:231], v[94:97]
	v_mfma_f32_16x16x32_bf16 v[90:93], v[138:141], v[228:231], v[90:93]
	v_mfma_f32_16x16x32_bf16 v[78:81], v[130:133], v[236:239], v[78:81]
	v_mfma_f32_16x16x32_bf16 v[74:77], v[138:141], v[236:239], v[74:77]
	v_mfma_f32_16x16x32_bf16 v[126:129], v[134:137], v[216:219], v[126:129]
	v_mfma_f32_16x16x32_bf16 v[122:125], v[142:145], v[216:219], v[122:125]
	v_mfma_f32_16x16x32_bf16 v[110:113], v[134:137], v[224:227], v[110:113]
	v_mfma_f32_16x16x32_bf16 v[106:109], v[142:145], v[224:227], v[106:109]
	v_mfma_f32_16x16x32_bf16 v[94:97], v[134:137], v[232:235], v[94:97]
	v_mfma_f32_16x16x32_bf16 v[90:93], v[142:145], v[232:235], v[90:93]
	v_mfma_f32_16x16x32_bf16 v[78:81], v[134:137], v[240:243], v[78:81]
	v_mfma_f32_16x16x32_bf16 v[74:77], v[142:145], v[240:243], v[74:77]
	s_setprio 0
	s_setprio 1
	v_mfma_f32_16x16x32_bf16 v[118:121], v[170:173], v[210:213], v[118:121]
	v_mfma_f32_16x16x32_bf16 v[114:117], v[202:205], v[210:213], v[114:117]
	v_mfma_f32_16x16x32_bf16 v[102:105], v[170:173], v[220:223], v[102:105]
	v_mfma_f32_16x16x32_bf16 v[98:101], v[202:205], v[220:223], v[98:101]
	v_mfma_f32_16x16x32_bf16 v[86:89], v[170:173], v[228:231], v[86:89]
	v_mfma_f32_16x16x32_bf16 v[82:85], v[202:205], v[228:231], v[82:85]
	v_mfma_f32_16x16x32_bf16 v[70:73], v[170:173], v[236:239], v[70:73]
	v_mfma_f32_16x16x32_bf16 v[66:69], v[202:205], v[236:239], v[66:69]
	v_mfma_f32_16x16x32_bf16 v[118:121], v[174:177], v[216:219], v[118:121]
	v_mfma_f32_16x16x32_bf16 v[114:117], v[206:209], v[216:219], v[114:117]
	v_mfma_f32_16x16x32_bf16 v[102:105], v[174:177], v[224:227], v[102:105]
	v_mfma_f32_16x16x32_bf16 v[98:101], v[206:209], v[224:227], v[98:101]
	v_mfma_f32_16x16x32_bf16 v[86:89], v[174:177], v[232:235], v[86:89]
	v_mfma_f32_16x16x32_bf16 v[82:85], v[206:209], v[232:235], v[82:85]
	v_mfma_f32_16x16x32_bf16 v[70:73], v[174:177], v[240:243], v[70:73]
	v_mfma_f32_16x16x32_bf16 v[66:69], v[206:209], v[240:243], v[66:69]
	s_setprio 0
	s_barrier
	s_add_i32 s30, s30, s61
	s_mov_b32 m0, s30
	ds_read_b128 v[210:213], v200 offset:16384
	ds_read_b128 v[216:219], v200 offset:17408
	ds_read_b128 v[220:223], v200 offset:18432
	ds_read_b128 v[224:227], v200 offset:19456
	ds_read_b128 v[228:231], v200 offset:20480
	ds_read_b128 v[232:235], v200 offset:21504
	ds_read_b128 v[236:239], v200 offset:22528
	ds_read_b128 v[240:243], v200 offset:23552
	global_load_lds_dwordx4 v154, s[10:11]
	s_add_i32 m0, s30, 0x2000
	s_add_u32 s42, s10, 0x40000
	s_addc_u32 s43, s11, 0
	s_add_i32 s30, s31, s61
	global_load_lds_dwordx4 v158, s[10:11]
	s_mov_b32 m0, s30
	s_nop 0
	global_load_lds_dwordx4 v154, s[42:43]
	s_add_i32 m0, s30, 0x2000
	s_nop 0
	global_load_lds_dwordx4 v158, s[42:43]
	s_mov_b32 m0, s59
	s_nop 0
	global_load_lds_dwordx4 v152, s[12:13]
	s_mov_b32 m0, s62
	s_nop 0
	global_load_lds_dwordx4 v156, s[12:13]
	s_waitcnt vmcnt(8)
	s_waitcnt lgkmcnt(0)
	s_barrier
	s_setprio 1
	s_waitcnt lgkmcnt(0)
	v_mfma_f32_16x16x32_bf16 v[62:65], v[130:133], v[210:213], v[62:65]
	v_mfma_f32_16x16x32_bf16 v[58:61], v[138:141], v[210:213], v[58:61]
	v_mfma_f32_16x16x32_bf16 v[46:49], v[130:133], v[220:223], v[46:49]
	v_mfma_f32_16x16x32_bf16 v[42:45], v[138:141], v[220:223], v[42:45]
	v_mfma_f32_16x16x32_bf16 v[30:33], v[130:133], v[228:231], v[30:33]
	v_mfma_f32_16x16x32_bf16 v[26:29], v[138:141], v[228:231], v[26:29]
	v_mfma_f32_16x16x32_bf16 v[14:17], v[130:133], v[236:239], v[14:17]
	v_mfma_f32_16x16x32_bf16 v[10:13], v[138:141], v[236:239], v[10:13]
	v_mfma_f32_16x16x32_bf16 v[62:65], v[134:137], v[216:219], v[62:65]
	v_mfma_f32_16x16x32_bf16 v[58:61], v[142:145], v[216:219], v[58:61]
	v_mfma_f32_16x16x32_bf16 v[46:49], v[134:137], v[224:227], v[46:49]
	v_mfma_f32_16x16x32_bf16 v[42:45], v[142:145], v[224:227], v[42:45]
	v_mfma_f32_16x16x32_bf16 v[30:33], v[134:137], v[232:235], v[30:33]
	v_mfma_f32_16x16x32_bf16 v[26:29], v[142:145], v[232:235], v[26:29]
	v_mfma_f32_16x16x32_bf16 v[14:17], v[134:137], v[240:243], v[14:17]
	v_mfma_f32_16x16x32_bf16 v[10:13], v[142:145], v[240:243], v[10:13]
	s_setprio 0
	s_setprio 1
	v_mfma_f32_16x16x32_bf16 v[54:57], v[170:173], v[210:213], v[54:57]
	v_mfma_f32_16x16x32_bf16 v[50:53], v[202:205], v[210:213], v[50:53]
	v_mfma_f32_16x16x32_bf16 v[38:41], v[170:173], v[220:223], v[38:41]
	v_mfma_f32_16x16x32_bf16 v[34:37], v[202:205], v[220:223], v[34:37]
	v_mfma_f32_16x16x32_bf16 v[22:25], v[170:173], v[228:231], v[22:25]
	v_mfma_f32_16x16x32_bf16 v[18:21], v[202:205], v[228:231], v[18:21]
	v_mfma_f32_16x16x32_bf16 v[6:9], v[170:173], v[236:239], v[6:9]
	v_mfma_f32_16x16x32_bf16 v[2:5], v[202:205], v[236:239], v[2:5]
	v_mfma_f32_16x16x32_bf16 v[54:57], v[174:177], v[216:219], v[54:57]
	v_mfma_f32_16x16x32_bf16 v[50:53], v[206:209], v[216:219], v[50:53]
	v_mfma_f32_16x16x32_bf16 v[38:41], v[174:177], v[224:227], v[38:41]
	v_mfma_f32_16x16x32_bf16 v[34:37], v[206:209], v[224:227], v[34:37]
	v_mfma_f32_16x16x32_bf16 v[22:25], v[174:177], v[232:235], v[22:25]
	v_mfma_f32_16x16x32_bf16 v[18:21], v[206:209], v[232:235], v[18:21]
	v_mfma_f32_16x16x32_bf16 v[6:9], v[174:177], v[240:243], v[6:9]
	v_mfma_f32_16x16x32_bf16 v[2:5], v[206:209], v[240:243], v[2:5]
	s_setprio 0
	s_barrier
	s_add_i32 s30, 0, 0x18000
	v_add_u32_e32 v0, s30, v197
	s_add_i32 s31, 0, 0x1c000
	ds_read_b128 v[130:133], v0
	ds_read_b128 v[134:137], v0 offset:1024
	ds_read_b128 v[138:141], v0 offset:2048
	ds_read_b128 v[142:145], v0 offset:3072
	v_add_u32_e32 v0, s31, v197
	ds_read_b128 v[170:173], v0
	ds_read_b128 v[174:177], v0 offset:1024
	ds_read_b128 v[202:205], v0 offset:2048
	ds_read_b128 v[206:209], v0 offset:3072
	s_add_u32 s12, s12, 0x40000
	s_addc_u32 s13, s13, 0
	s_mov_b32 m0, s63
	ds_read_b128 v[210:213], v200 offset:32768
	ds_read_b128 v[216:219], v200 offset:33792
	ds_read_b128 v[220:223], v200 offset:34816
	ds_read_b128 v[224:227], v200 offset:35840
	ds_read_b128 v[228:231], v200 offset:36864
	ds_read_b128 v[232:235], v200 offset:37888
	ds_read_b128 v[236:239], v200 offset:38912
	ds_read_b128 v[240:243], v200 offset:39936
	global_load_lds_dwordx4 v152, s[12:13]
	s_mov_b32 m0, s64
	s_nop 0
	global_load_lds_dwordx4 v156, s[12:13]
	s_waitcnt vmcnt(8)
	s_waitcnt lgkmcnt(0)
	s_barrier
	s_setprio 1
	s_waitcnt lgkmcnt(0)
	v_mfma_f32_16x16x32_bf16 v[126:129], v[130:133], v[210:213], v[126:129]
	v_mfma_f32_16x16x32_bf16 v[122:125], v[138:141], v[210:213], v[122:125]
	v_mfma_f32_16x16x32_bf16 v[110:113], v[130:133], v[220:223], v[110:113]
	v_mfma_f32_16x16x32_bf16 v[106:109], v[138:141], v[220:223], v[106:109]
	v_mfma_f32_16x16x32_bf16 v[94:97], v[130:133], v[228:231], v[94:97]
	v_mfma_f32_16x16x32_bf16 v[90:93], v[138:141], v[228:231], v[90:93]
	v_mfma_f32_16x16x32_bf16 v[78:81], v[130:133], v[236:239], v[78:81]
	v_mfma_f32_16x16x32_bf16 v[74:77], v[138:141], v[236:239], v[74:77]
	v_mfma_f32_16x16x32_bf16 v[126:129], v[134:137], v[216:219], v[126:129]
	v_mfma_f32_16x16x32_bf16 v[122:125], v[142:145], v[216:219], v[122:125]
	v_mfma_f32_16x16x32_bf16 v[110:113], v[134:137], v[224:227], v[110:113]
	v_mfma_f32_16x16x32_bf16 v[106:109], v[142:145], v[224:227], v[106:109]
	v_mfma_f32_16x16x32_bf16 v[94:97], v[134:137], v[232:235], v[94:97]
	v_mfma_f32_16x16x32_bf16 v[90:93], v[142:145], v[232:235], v[90:93]
	v_mfma_f32_16x16x32_bf16 v[78:81], v[134:137], v[240:243], v[78:81]
	v_mfma_f32_16x16x32_bf16 v[74:77], v[142:145], v[240:243], v[74:77]
	s_setprio 0
	s_setprio 1
	v_mfma_f32_16x16x32_bf16 v[118:121], v[170:173], v[210:213], v[118:121]
	v_mfma_f32_16x16x32_bf16 v[114:117], v[202:205], v[210:213], v[114:117]
	v_mfma_f32_16x16x32_bf16 v[102:105], v[170:173], v[220:223], v[102:105]
	v_mfma_f32_16x16x32_bf16 v[98:101], v[202:205], v[220:223], v[98:101]
	v_mfma_f32_16x16x32_bf16 v[86:89], v[170:173], v[228:231], v[86:89]
	v_mfma_f32_16x16x32_bf16 v[82:85], v[202:205], v[228:231], v[82:85]
	v_mfma_f32_16x16x32_bf16 v[70:73], v[170:173], v[236:239], v[70:73]
	v_mfma_f32_16x16x32_bf16 v[66:69], v[202:205], v[236:239], v[66:69]
	v_mfma_f32_16x16x32_bf16 v[118:121], v[174:177], v[216:219], v[118:121]
	v_mfma_f32_16x16x32_bf16 v[114:117], v[206:209], v[216:219], v[114:117]
	v_mfma_f32_16x16x32_bf16 v[102:105], v[174:177], v[224:227], v[102:105]
	v_mfma_f32_16x16x32_bf16 v[98:101], v[206:209], v[224:227], v[98:101]
	v_mfma_f32_16x16x32_bf16 v[86:89], v[174:177], v[232:235], v[86:89]
	v_mfma_f32_16x16x32_bf16 v[82:85], v[206:209], v[232:235], v[82:85]
	v_mfma_f32_16x16x32_bf16 v[70:73], v[174:177], v[240:243], v[70:73]
	v_mfma_f32_16x16x32_bf16 v[66:69], v[206:209], v[240:243], v[66:69]
	s_setprio 0
	s_barrier
	s_add_i32 m0, s30, s61
	s_add_u32 s42, s10, 0x80
	s_addc_u32 s43, s11, 0
	ds_read_b128 v[210:213], v200 offset:49152
	ds_read_b128 v[216:219], v200 offset:50176
	ds_read_b128 v[220:223], v200 offset:51200
	ds_read_b128 v[224:227], v200 offset:52224
	ds_read_b128 v[228:231], v200 offset:53248
	ds_read_b128 v[232:235], v200 offset:54272
	ds_read_b128 v[236:239], v200 offset:55296
	ds_read_b128 v[240:243], v200 offset:56320
	global_load_lds_dwordx4 v154, s[42:43]
	s_add_i32 m0, m0, 0x2000
	s_add_u32 s10, s10, 0x40080
	s_addc_u32 s11, s11, 0
	global_load_lds_dwordx4 v158, s[42:43]
	s_add_i32 m0, s31, s61
	s_add_u32 s42, s12, 0xfffc0080
	s_addc_u32 s43, s13, -1
	global_load_lds_dwordx4 v154, s[10:11]
	s_add_i32 m0, m0, 0x2000
	s_nop 0
	global_load_lds_dwordx4 v158, s[10:11]
	s_mov_b32 m0, s66
	s_nop 0
	global_load_lds_dwordx4 v152, s[42:43]
	s_mov_b32 m0, s67
	s_add_i32 s12, s31, s61
	global_load_lds_dwordx4 v156, s[42:43]
	s_add_i32 s29, s29, 2
	s_add_u32 s8, s8, 0x100
	s_addc_u32 s9, s9, 0
	s_add_u32 s27, s27, 0x100
	s_addc_u32 s28, s28, 0
	s_cmp_gt_u32 s29, 13
	s_cbranch_scc1 .Lk1_skip
	s_add_u32 s10, s8, 0xfffc0080
	s_addc_u32 s11, s9, -1
	s_add_i32 s30, 0, 0x10000
	s_cmp_eq_u32 s29, 12
	s_cselect_b32 s13, s3, s11
	s_cselect_b32 s12, s24, s10
	s_cselect_b32 s11, s25, s28
	s_cselect_b32 s10, s26, s27
	s_add_i32 s31, 0, 0x14000
.Lk1_skip:
	s_waitcnt vmcnt(8)
	s_waitcnt lgkmcnt(0)
	s_barrier
	s_setprio 1
	s_waitcnt lgkmcnt(0)
	v_mfma_f32_16x16x32_bf16 v[62:65], v[130:133], v[210:213], v[62:65]
	v_mfma_f32_16x16x32_bf16 v[58:61], v[138:141], v[210:213], v[58:61]
	v_mfma_f32_16x16x32_bf16 v[46:49], v[130:133], v[220:223], v[46:49]
	v_mfma_f32_16x16x32_bf16 v[42:45], v[138:141], v[220:223], v[42:45]
	v_mfma_f32_16x16x32_bf16 v[30:33], v[130:133], v[228:231], v[30:33]
	v_mfma_f32_16x16x32_bf16 v[26:29], v[138:141], v[228:231], v[26:29]
	v_mfma_f32_16x16x32_bf16 v[14:17], v[130:133], v[236:239], v[14:17]
	v_mfma_f32_16x16x32_bf16 v[10:13], v[138:141], v[236:239], v[10:13]
	v_mfma_f32_16x16x32_bf16 v[62:65], v[134:137], v[216:219], v[62:65]
	v_mfma_f32_16x16x32_bf16 v[58:61], v[142:145], v[216:219], v[58:61]
	v_mfma_f32_16x16x32_bf16 v[46:49], v[134:137], v[224:227], v[46:49]
	v_mfma_f32_16x16x32_bf16 v[42:45], v[142:145], v[224:227], v[42:45]
	v_mfma_f32_16x16x32_bf16 v[30:33], v[134:137], v[232:235], v[30:33]
	v_mfma_f32_16x16x32_bf16 v[26:29], v[142:145], v[232:235], v[26:29]
	v_mfma_f32_16x16x32_bf16 v[14:17], v[134:137], v[240:243], v[14:17]
	v_mfma_f32_16x16x32_bf16 v[10:13], v[142:145], v[240:243], v[10:13]
	s_setprio 0
	s_setprio 1
	v_mfma_f32_16x16x32_bf16 v[54:57], v[170:173], v[210:213], v[54:57]
	v_mfma_f32_16x16x32_bf16 v[50:53], v[202:205], v[210:213], v[50:53]
	v_mfma_f32_16x16x32_bf16 v[38:41], v[170:173], v[220:223], v[38:41]
	v_mfma_f32_16x16x32_bf16 v[34:37], v[202:205], v[220:223], v[34:37]
	v_mfma_f32_16x16x32_bf16 v[22:25], v[170:173], v[228:231], v[22:25]
	v_mfma_f32_16x16x32_bf16 v[18:21], v[202:205], v[228:231], v[18:21]
	v_mfma_f32_16x16x32_bf16 v[6:9], v[170:173], v[236:239], v[6:9]
	v_mfma_f32_16x16x32_bf16 v[2:5], v[202:205], v[236:239], v[2:5]
	v_mfma_f32_16x16x32_bf16 v[54:57], v[174:177], v[216:219], v[54:57]
	v_mfma_f32_16x16x32_bf16 v[50:53], v[206:209], v[216:219], v[50:53]
	v_mfma_f32_16x16x32_bf16 v[38:41], v[174:177], v[224:227], v[38:41]
	v_mfma_f32_16x16x32_bf16 v[34:37], v[206:209], v[224:227], v[34:37]
	v_mfma_f32_16x16x32_bf16 v[22:25], v[174:177], v[232:235], v[22:25]
	v_mfma_f32_16x16x32_bf16 v[18:21], v[206:209], v[232:235], v[18:21]
	v_mfma_f32_16x16x32_bf16 v[6:9], v[174:177], v[240:243], v[6:9]
	v_mfma_f32_16x16x32_bf16 v[2:5], v[206:209], v[240:243], v[2:5]
	s_setprio 0
	s_barrier
	s_cmp_gt_u32 s29, 13
	s_cbranch_scc0 .Lk1_body
	s_and_b64 vcc, exec, s[46:47]
	s_cbranch_vccz .LBB0_173
	s_barrier
